# v4 + x-prep row loads issued together + sc_conv walker: eight row loads per 4-row iteration issued up front (counted vmcnt)
# speedup vs baseline: 1.0409x; 1.0049x over previous
; __device__ __forceinline__ unsigned pk2(float lo, float hi) { unsigned r; asm volatile("v_cvt_pk_bf16_f32 %0, %1, %2" : "=v"(r) : "v"(lo), "v"(hi)); return r; }
; __device__ __forceinline__ void phase_prep(const Args& a, float* ldsf) {
;     ...
;     for (int row = gw; row < M_; row += NGW) {
;         float s2 = 0.f;
; #pragma unroll
;         for (int jj = 0; jj < 4; ++jj) {
;             const size_t idx = (size_t)row * 1024 + 256 * jj + 4 * lane;
;             const f32x4 v = *(const f32x4*)(x + idx);
;             u32x2 w; w.x = pk2(v[0], v[1]); w.y = pk2(v[2], v[3]); *(u32x2*)(XB + idx) = w;
;             s2 += (v[0] * v[0] + v[1] * v[1]) + (v[2] * v[2] + v[3] * v[3]);
;         }
;         s2 = wave_sum(s2);
;         if (lane == 0) *(f32x4*)(RSX + (size_t)row * 4) = (f32x4){s2, 0.f, 0.f, 0.f};
;     }
.LBB0_551:
	v_lshl_add_u64 v[4:5], s[30:31], 0, v[14:15]
	v_add_co_u32_e32 v4, vcc, 0x7300000, v4
	global_load_dwordx4 v[18:21], v[16:17], off offset:-2048
	global_load_dwordx4 v[22:25], v[16:17], off offset:-1024
	v_addc_co_u32_e32 v5, vcc, 0, v5, vcc
	global_load_dwordx4 v[26:29], v[16:17], off
	global_load_dwordx4 v[30:33], v[16:17], off offset:1024
	s_waitcnt vmcnt(3)
	v_cvt_pk_bf16_f32 v34, v18, v19
	v_cvt_pk_bf16_f32 v35, v20, v21
	global_store_dwordx2 v[4:5], v[34:35], off
	s_waitcnt vmcnt(3)
	v_cvt_pk_bf16_f32 v36, v22, v23
	v_cvt_pk_bf16_f32 v37, v24, v25
	global_store_dwordx2 v[4:5], v[36:37], off offset:512
	s_waitcnt vmcnt(3)
	v_cvt_pk_bf16_f32 v38, v26, v27
	v_cvt_pk_bf16_f32 v39, v28, v29
	global_store_dwordx2 v[4:5], v[38:39], off offset:1024
	v_cmp_lt_i32_e32 vcc, v209, v208
	s_waitcnt lgkmcnt(0)
	v_mul_f32_e32 v2, v19, v19
	v_mul_f32_e32 v11, v21, v21
	v_fmac_f32_e32 v2, v18, v18
	v_fmac_f32_e32 v11, v20, v20
	v_add_f32_e32 v2, v2, v11
	v_cndmask_b32_e32 v1, v207, v209, vcc
	v_mul_f32_e32 v11, v23, v23
	v_mul_f32_e32 v18, v25, v25
	v_fmac_f32_e32 v11, v22, v22
	v_fmac_f32_e32 v18, v24, v24
	v_add_f32_e32 v11, v11, v18
	v_add_f32_e32 v2, v2, v11
	v_mul_f32_e32 v11, v27, v27
	v_mul_f32_e32 v18, v29, v29
	v_fmac_f32_e32 v11, v26, v26
	v_fmac_f32_e32 v18, v28, v28
	v_add_f32_e32 v11, v11, v18
	v_add_f32_e32 v2, v2, v11
	s_waitcnt vmcnt(3)
	v_mul_f32_e32 v11, v31, v31
	v_mul_f32_e32 v18, v33, v33
	v_fmac_f32_e32 v11, v30, v30
	v_fmac_f32_e32 v18, v32, v32
	v_add_f32_e32 v11, v11, v18
	v_lshlrev_b32_e32 v1, 2, v1
	v_add_f32_e32 v2, v2, v11
	ds_bpermute_b32 v1, v1, v2
	v_cmp_lt_i32_e32 vcc, v210, v208
	v_cvt_pk_bf16_f32 v18, v30, v31
	v_cvt_pk_bf16_f32 v19, v32, v33
	global_store_dwordx2 v[4:5], v[18:19], off offset:1536
	s_waitcnt lgkmcnt(0)
	v_add_f32_e32 v1, v2, v1
	v_cndmask_b32_e32 v11, v207, v210, vcc
	v_lshlrev_b32_e32 v11, 2, v11
	ds_bpermute_b32 v2, v11, v1
	v_cmp_lt_i32_e32 vcc, v211, v208
	s_waitcnt lgkmcnt(0)
	v_add_f32_e32 v1, v1, v2
	v_cndmask_b32_e32 v11, v207, v211, vcc
	v_lshlrev_b32_e32 v11, 2, v11
	ds_bpermute_b32 v2, v11, v1
	v_cmp_lt_i32_e32 vcc, v212, v208
	s_waitcnt lgkmcnt(0)
	v_add_f32_e32 v1, v1, v2
	v_cndmask_b32_e32 v11, v207, v212, vcc
	v_lshlrev_b32_e32 v11, 2, v11
	ds_bpermute_b32 v2, v11, v1
	v_cmp_lt_i32_e32 vcc, v213, v208
	s_waitcnt lgkmcnt(0)
	v_add_f32_e32 v1, v1, v2
	v_cndmask_b32_e32 v11, v207, v213, vcc
	v_lshlrev_b32_e32 v11, 2, v11
	ds_bpermute_b32 v2, v11, v1
	v_cmp_lt_i32_e32 vcc, v214, v208
	s_waitcnt lgkmcnt(0)
	v_add_f32_e32 v1, v1, v2
	v_cndmask_b32_e32 v11, v207, v214, vcc
	v_lshlrev_b32_e32 v2, 2, v11
	ds_bpermute_b32 v2, v2, v1
	s_and_saveexec_b64 s[8:9], s[0:1]
	s_cbranch_execz .LBB0_550
	s_waitcnt lgkmcnt(0)
	v_add_f32_e32 v2, v1, v2
	v_lshl_add_u64 v[18:19], s[30:31], 0, v[12:13]
	v_mov_b32_e32 v4, v3
	v_mov_b32_e32 v5, v3
	global_store_dwordx4 v[18:19], v[2:5], off
	s_branch .LBB0_550

; __device__ __forceinline__ uint4 pack8(const float* f) { uint4 o; o.x = pk2(f[0], f[1]); o.y = pk2(f[2], f[3]); o.z = pk2(f[4], f[5]); o.w = pk2(f[6], f[7]); return o; }
; __device__ __forceinline__ void phase_sc_conv(const Args& a, int j) {
;     ...
; #pragma unroll 4
;         for (int r = 0; r < RUN; ++r) {
;             bf16_t* p = BIG + (size_t)(row0 + r) * LD + c0;
;             float gb[8], cur[8], o[8];
;             unpack8(*(const uint4*)p, gb); unpack8(*(const uint4*)(p + 1024), cur);
; #pragma unroll
;             for (int e = 0; e < 8; ++e) { o[e] = gb[e] * (w0[e] * g0[e] + w1[e] * g1[e] + w2[e] * cur[e]); g0[e] = g1[e]; g1[e] = cur[e]; }
;             *(uint4*)p = pack8(o);
;         }
.LBB0_760:
	v_lshl_add_u64 v[38:39], v[4:5], 0, s[12:13]
	v_add_co_u32_e32 v50, vcc, s26, v38
	s_mov_b32 s2, 0x9302000
	s_nop 0
	v_addc_co_u32_e32 v51, vcc, 0, v39, vcc
	v_add_co_u32_e32 v40, vcc, s18, v38
	s_add_u32 s12, s12, 0x4000
	s_nop 0
	v_addc_co_u32_e32 v41, vcc, 0, v39, vcc
	v_add_co_u32_e32 v108, vcc, 0x9303000, v38
	s_nop 1
	v_addc_co_u32_e32 v109, vcc, 0, v39, vcc
	global_load_dwordx4 v[76:79], v[40:41], off offset:-4096
	global_load_dwordx4 v[80:83], v[40:41], off offset:-2048
	global_load_dwordx4 v[84:87], v[40:41], off
	global_load_dwordx4 v[88:91], v[40:41], off offset:2048
	global_load_dwordx4 v[92:95], v[108:109], off offset:-4096
	global_load_dwordx4 v[96:99], v[108:109], off offset:-2048
	global_load_dwordx4 v[100:103], v[108:109], off
	global_load_dwordx4 v[104:107], v[108:109], off offset:2048
	s_addc_u32 s13, s13, 0
	s_cmp_eq_u32 s12, 0x10000
	s_waitcnt vmcnt(7)
	v_lshlrev_b32_e32 v53, 16, v76
	v_and_b32_e32 v54, 0xffff0000, v76
	v_lshlrev_b32_e32 v69, 16, v77
	v_and_b32_e32 v70, 0xffff0000, v77
	v_lshlrev_b32_e32 v71, 16, v78
	v_and_b32_e32 v72, 0xffff0000, v78
	v_lshlrev_b32_e32 v73, 16, v79
	v_and_b32_e32 v74, 0xffff0000, v79
	s_waitcnt vmcnt(6)
	v_lshlrev_b32_e32 v60, 16, v80
	v_and_b32_e32 v59, 0xffff0000, v80
	v_mul_f32_e32 v46, v22, v62
	v_fmac_f32_e32 v46, v14, v44
	v_mul_f32_e32 v44, v23, v67
	v_fmac_f32_e32 v46, v30, v60
	v_fmac_f32_e32 v44, v15, v43
	v_mul_f32_e32 v43, v46, v53
	v_mul_f32_e32 v46, v24, v65
	v_lshlrev_b32_e32 v58, 16, v81
	v_fmac_f32_e32 v46, v16, v42
	v_mul_f32_e32 v42, v25, v66
	v_fmac_f32_e32 v46, v32, v58
	v_fmac_f32_e32 v42, v17, v2
	v_mul_f32_e32 v2, v46, v69
	v_mul_f32_e32 v46, v18, v63
	v_lshlrev_b32_e32 v56, 16, v82
	v_fmac_f32_e32 v46, v10, v36
	v_mul_f32_e32 v36, v19, v64
	v_fmac_f32_e32 v46, v26, v56
	v_fmac_f32_e32 v36, v11, v37
	v_mul_f32_e32 v37, v46, v71
	v_mul_f32_e32 v46, v20, v61
	v_and_b32_e32 v55, 0xffff0000, v82
	v_fmac_f32_e32 v46, v12, v34
	v_mul_f32_e32 v34, v21, v68
	v_and_b32_e32 v57, 0xffff0000, v81
	v_lshlrev_b32_e32 v52, 16, v83
	v_and_b32_e32 v45, 0xffff0000, v83
	v_fmac_f32_e32 v36, v27, v55
	v_fmac_f32_e32 v34, v13, v35
	v_fmac_f32_e32 v44, v31, v59
	v_fmac_f32_e32 v42, v33, v57
	v_mul_f32_e32 v36, v36, v72
	v_fmac_f32_e32 v46, v28, v52
	v_fmac_f32_e32 v34, v29, v45
	v_mul_f32_e32 v44, v44, v54
	v_mul_f32_e32 v42, v42, v70
	v_mul_f32_e32 v46, v46, v73
	v_mul_f32_e32 v47, v34, v74
	v_cvt_pk_bf16_f32 v34, v43, v44
	v_cvt_pk_bf16_f32 v35, v2, v42
	v_cvt_pk_bf16_f32 v36, v37, v36
	v_cvt_pk_bf16_f32 v37, v46, v47
	global_store_dwordx4 v[40:41], v[34:37], off offset:-4096
	s_waitcnt vmcnt(6)
	v_lshlrev_b32_e32 v2, 16, v84
	v_and_b32_e32 v42, 0xffff0000, v84
	v_lshlrev_b32_e32 v43, 16, v85
	v_and_b32_e32 v44, 0xffff0000, v85
	v_lshlrev_b32_e32 v69, 16, v86
	v_and_b32_e32 v70, 0xffff0000, v86
	v_lshlrev_b32_e32 v71, 16, v87
	v_and_b32_e32 v72, 0xffff0000, v87
	s_waitcnt vmcnt(5)
	v_lshlrev_b32_e32 v54, 16, v88
	v_and_b32_e32 v53, 0xffff0000, v88
	v_lshlrev_b32_e32 v51, 16, v89
	v_and_b32_e32 v50, 0xffff0000, v89
	v_mul_f32_e32 v34, v22, v60
	v_mul_f32_e32 v35, v23, v59
	v_fmac_f32_e32 v34, v14, v62
	v_fmac_f32_e32 v35, v15, v67
	v_fmac_f32_e32 v34, v30, v54
	v_fmac_f32_e32 v35, v31, v53
	v_mul_f32_e32 v2, v34, v2
	v_mul_f32_e32 v34, v35, v42
	v_mul_f32_e32 v35, v24, v58
	v_lshlrev_b32_e32 v49, 16, v90
	v_and_b32_e32 v48, 0xffff0000, v90
	v_fmac_f32_e32 v35, v16, v65
	v_mul_f32_e32 v36, v25, v57
	v_fmac_f32_e32 v36, v17, v66
	v_fmac_f32_e32 v35, v32, v51
	v_mul_f32_e32 v42, v19, v55
	v_lshlrev_b32_e32 v47, 16, v91
	v_and_b32_e32 v46, 0xffff0000, v91
	v_mul_f32_e32 v35, v35, v43
	v_fmac_f32_e32 v36, v33, v50
	v_mul_f32_e32 v37, v18, v56
	v_fmac_f32_e32 v42, v11, v64
	v_mul_f32_e32 v43, v20, v52
	v_mul_f32_e32 v36, v36, v44
	v_fmac_f32_e32 v37, v10, v63
	v_fmac_f32_e32 v42, v27, v48
	v_fmac_f32_e32 v43, v12, v61
	v_mul_f32_e32 v44, v21, v45
	v_fmac_f32_e32 v37, v26, v49
	v_mul_f32_e32 v42, v42, v70
	v_fmac_f32_e32 v44, v13, v68
	v_fmac_f32_e32 v43, v28, v47
	v_mul_f32_e32 v37, v37, v69
	v_mul_f32_e32 v43, v43, v71
	v_fmac_f32_e32 v44, v29, v46
	v_cvt_pk_bf16_f32 v34, v2, v34
	v_cvt_pk_bf16_f32 v35, v35, v36
	v_cvt_pk_bf16_f32 v36, v37, v42
	v_add_co_u32_e32 v42, vcc, s2, v38
	v_mul_f32_e32 v44, v44, v72
	v_cvt_pk_bf16_f32 v37, v43, v44
	s_nop 0
	v_addc_co_u32_e32 v43, vcc, 0, v39, vcc
	s_mov_b32 s2, 0x9303000
	v_add_co_u32_e32 v38, vcc, s2, v38
	global_store_dwordx4 v[40:41], v[34:37], off
	s_nop 0
	v_addc_co_u32_e32 v39, vcc, 0, v39, vcc
	s_waitcnt vmcnt(5)
; __device__ __forceinline__ uint4 pack8(const float* f) { uint4 o; o.x = pk2(f[0], f[1]); o.y = pk2(f[2], f[3]); o.z = pk2(f[4], f[5]); o.w = pk2(f[6], f[7]); return o; }
; __device__ __forceinline__ void phase_sc_conv(const Args& a, int j) {
;     ...
; #pragma unroll 4
;         for (int r = 0; r < RUN; ++r) {
;             bf16_t* p = BIG + (size_t)(row0 + r) * LD + c0;
;             float gb[8], cur[8], o[8];
;             unpack8(*(const uint4*)p, gb); unpack8(*(const uint4*)(p + 1024), cur);
; #pragma unroll
;             for (int e = 0; e < 8; ++e) { o[e] = gb[e] * (w0[e] * g0[e] + w1[e] * g1[e] + w2[e] * cur[e]); g0[e] = g1[e]; g1[e] = cur[e]; }
;             *(uint4*)p = pack8(o);
;         }
	v_lshlrev_b32_e32 v65, 16, v92
	s_waitcnt vmcnt(4)
	v_lshlrev_b32_e32 v44, 16, v96
	v_and_b32_e32 v43, 0xffff0000, v96
	v_mul_f32_e32 v66, v22, v54
	v_fmac_f32_e32 v66, v14, v60
	v_mul_f32_e32 v60, v23, v53
	v_fmac_f32_e32 v66, v30, v44
	v_fmac_f32_e32 v60, v15, v59
	v_mul_f32_e32 v59, v66, v65
	v_mul_f32_e32 v65, v24, v51
	v_fmac_f32_e32 v65, v16, v58
	v_mul_f32_e32 v58, v25, v50
	v_and_b32_e32 v2, 0xffff0000, v97
	v_fmac_f32_e32 v58, v17, v57
	v_and_b32_e32 v63, 0xffff0000, v93
	v_fmac_f32_e32 v58, v33, v2
	v_mul_f32_e32 v58, v58, v63
	v_mul_f32_e32 v63, v18, v49
	v_fmac_f32_e32 v63, v10, v56
	v_mul_f32_e32 v56, v19, v48
	v_lshlrev_b32_e32 v41, 16, v95
	v_and_b32_e32 v40, 0xffff0000, v95
	v_and_b32_e32 v37, 0xffff0000, v98
	v_fmac_f32_e32 v56, v11, v55
	v_and_b32_e32 v61, 0xffff0000, v94
	v_fmac_f32_e32 v56, v27, v37
	v_mul_f32_e32 v61, v56, v61
	v_mul_f32_e32 v56, v20, v47
	v_lshlrev_b32_e32 v42, 16, v97
	v_fmac_f32_e32 v56, v12, v52
	v_mul_f32_e32 v52, v21, v46
	v_and_b32_e32 v70, 0xffff0000, v92
	v_lshlrev_b32_e32 v64, 16, v93
	v_lshlrev_b32_e32 v62, 16, v94
	v_lshlrev_b32_e32 v36, 16, v98
	v_lshlrev_b32_e32 v34, 16, v99
	v_and_b32_e32 v35, 0xffff0000, v99
	v_fmac_f32_e32 v65, v32, v42
	v_fmac_f32_e32 v52, v13, v45
	v_fmac_f32_e32 v60, v31, v43
	v_mul_f32_e32 v57, v65, v64
	v_fmac_f32_e32 v63, v26, v36
	v_fmac_f32_e32 v56, v28, v34
	v_fmac_f32_e32 v52, v29, v35
	v_mul_f32_e32 v60, v60, v70
	v_mul_f32_e32 v55, v63, v62
	v_mul_f32_e32 v41, v56, v41
	v_mul_f32_e32 v40, v52, v40
	v_cvt_pk_bf16_f32 v56, v59, v60
	v_cvt_pk_bf16_f32 v57, v57, v58
	v_cvt_pk_bf16_f32 v58, v55, v61
	v_cvt_pk_bf16_f32 v59, v41, v40
	global_store_dwordx4 v[38:39], v[56:59], off offset:-4096
	s_waitcnt vmcnt(4)
	v_lshlrev_b32_e32 v40, 16, v100
	v_and_b32_e32 v41, 0xffff0000, v100
	v_lshlrev_b32_e32 v45, 16, v101
	v_and_b32_e32 v52, 0xffff0000, v101
	v_lshlrev_b32_e32 v55, 16, v102
	v_and_b32_e32 v60, 0xffff0000, v102
	v_lshlrev_b32_e32 v69, 16, v103
	v_and_b32_e32 v70, 0xffff0000, v103
	s_waitcnt vmcnt(3)
	v_lshlrev_b32_e32 v62, 16, v104
	v_and_b32_e32 v67, 0xffff0000, v104
	v_mul_f32_e32 v56, v22, v44
	v_fmac_f32_e32 v56, v14, v54
	v_mul_f32_e32 v54, v23, v43
	v_fmac_f32_e32 v54, v15, v53
	v_mul_f32_e32 v53, v24, v42
	v_fmac_f32_e32 v53, v16, v51
	v_mul_f32_e32 v51, v25, v2
	v_and_b32_e32 v66, 0xffff0000, v105
	v_fmac_f32_e32 v51, v17, v50
	v_fmac_f32_e32 v51, v33, v66
	v_mul_f32_e32 v50, v51, v52
	v_mul_f32_e32 v51, v18, v36
	v_lshlrev_b32_e32 v63, 16, v106
	v_fmac_f32_e32 v51, v10, v49
	v_mul_f32_e32 v49, v19, v37
	v_fmac_f32_e32 v51, v26, v63
	v_fmac_f32_e32 v49, v11, v48
	v_mul_f32_e32 v48, v51, v55
	v_mul_f32_e32 v51, v20, v34
	v_and_b32_e32 v64, 0xffff0000, v106
	v_fmac_f32_e32 v51, v12, v47
	v_mul_f32_e32 v47, v21, v35
	v_lshlrev_b32_e32 v65, 16, v105
	v_lshlrev_b32_e32 v61, 16, v107
	v_and_b32_e32 v68, 0xffff0000, v107
	v_fmac_f32_e32 v49, v27, v64
	v_fmac_f32_e32 v47, v13, v46
	v_fmac_f32_e32 v56, v30, v62
	v_fmac_f32_e32 v54, v31, v67
	v_fmac_f32_e32 v53, v32, v65
	v_mul_f32_e32 v49, v49, v60
	v_fmac_f32_e32 v51, v28, v61
	v_fmac_f32_e32 v47, v29, v68
	v_mul_f32_e32 v40, v56, v40
	v_mul_f32_e32 v41, v54, v41
	v_mul_f32_e32 v45, v53, v45
	v_mul_f32_e32 v51, v51, v69
	v_mul_f32_e32 v52, v47, v70
	v_cvt_pk_bf16_f32 v46, v40, v41
	v_cvt_pk_bf16_f32 v47, v45, v50
	v_cvt_pk_bf16_f32 v48, v48, v49
	v_cvt_pk_bf16_f32 v49, v51, v52
	global_store_dwordx4 v[38:39], v[46:49], off
	s_cbranch_scc0 .LBB0_760
	v_add_u32_e32 v1, s90, v1
	s_mov_b32 s2, 0x1ffff
	v_cmp_lt_i32_e32 vcc, s2, v1
	s_or_b64 s[10:11], vcc, s[10:11]
	s_andn2_b64 exec, exec, s[10:11]
	s_cbranch_execnz .LBB0_757
